# v10 + grid barrier: non-leader workgroups poll the cross-XCD release generation word directly instead of their XCD leader's relay word
# speedup vs baseline: 1.0105x; 1.0070x over previous
.LBB0_116:
	s_or_b64 exec, exec, s[8:9]
	v_cvt_f32_u32_e32 v4, v2
	s_waitcnt vmcnt(0)
	v_readfirstlane_b32 s6, v3
	v_sub_u32_e32 v3, 0, v2
	v_rcp_iflag_f32_e32 v4, v4
	v_add_u32_e32 v5, s6, v1
	v_mul_f32_e32 v4, 0x4f7ffffe, v4
	v_cvt_u32_f32_e32 v4, v4
	v_mul_lo_u32 v1, v3, v4
	v_mul_hi_u32 v1, v4, v1
	v_add_u32_e32 v1, v4, v1
	v_mul_hi_u32 v1, v5, v1
	v_mul_lo_u32 v3, v1, v2
	v_sub_u32_e32 v3, v5, v3
	v_add_u32_e32 v4, 1, v1
	v_cmp_ge_u32_e32 vcc, v3, v2
	s_nop 1
	v_cndmask_b32_e32 v1, v1, v4, vcc
	v_sub_u32_e32 v4, v3, v2
	v_cndmask_b32_e32 v3, v3, v4, vcc
	v_add_u32_e32 v4, 1, v1
	v_cmp_ge_u32_e32 vcc, v3, v2
	v_add_u32_e32 v3, 1, v5
	s_nop 0
	v_cndmask_b32_e32 v1, v1, v4, vcc
	v_mul_lo_u32 v4, v2, v1
	v_add_u32_e32 v2, v4, v2
	v_cmp_ne_u32_e32 vcc, v3, v2
	s_and_saveexec_b64 s[6:7], vcc
	s_xor_b64 s[6:7], exec, s[6:7]
	s_cbranch_execz .LBB0_130
	s_waitcnt lgkmcnt(0)
	v_mov_b32_e32 v0, 0x7500
	global_load_dword v0, v0, s[84:85] sc1
	s_add_u32 s12, s84, 0x7500
	s_addc_u32 s13, s85, 0
	s_waitcnt vmcnt(0)
	v_cmp_eq_u32_e32 vcc, v0, v1
	s_and_saveexec_b64 s[8:9], vcc
	s_cbranch_execz .LBB0_129
	s_add_u32 s10, s84, 0x4200
	s_addc_u32 s11, s85, 0
	s_mov_b32 s23, 1
	s_mov_b64 s[14:15], 0
	v_mov_b32_e32 v0, 0
	s_branch .LBB0_120

.LBB0_231:
	s_or_b64 exec, exec, s[8:9]
	v_cvt_f32_u32_e32 v4, v2
	s_waitcnt vmcnt(0)
	v_readfirstlane_b32 s3, v3
	v_sub_u32_e32 v3, 0, v2
	v_rcp_iflag_f32_e32 v4, v4
	v_add_u32_e32 v5, s3, v1
	v_mul_f32_e32 v4, 0x4f7ffffe, v4
	v_cvt_u32_f32_e32 v4, v4
	v_mul_lo_u32 v1, v3, v4
	v_mul_hi_u32 v1, v4, v1
	v_add_u32_e32 v1, v4, v1
	v_mul_hi_u32 v1, v5, v1
	v_mul_lo_u32 v3, v1, v2
	v_sub_u32_e32 v3, v5, v3
	v_add_u32_e32 v4, 1, v1
	v_cmp_ge_u32_e32 vcc, v3, v2
	s_nop 1
	v_cndmask_b32_e32 v1, v1, v4, vcc
	v_sub_u32_e32 v4, v3, v2
	v_cndmask_b32_e32 v3, v3, v4, vcc
	v_add_u32_e32 v4, 1, v1
	v_cmp_ge_u32_e32 vcc, v3, v2
	v_add_u32_e32 v3, 1, v5
	s_nop 0
	v_cndmask_b32_e32 v1, v1, v4, vcc
	v_mul_lo_u32 v4, v2, v1
	v_add_u32_e32 v2, v4, v2
	v_cmp_ne_u32_e32 vcc, v3, v2
	s_and_saveexec_b64 s[6:7], vcc
	s_xor_b64 s[6:7], exec, s[6:7]
	s_cbranch_execz .LBB0_245
	s_waitcnt lgkmcnt(0)
	v_mov_b32_e32 v0, 0x7500
	global_load_dword v0, v0, s[84:85] sc1
	s_add_u32 s14, s84, 0x7500
	s_addc_u32 s15, s85, 0
	s_waitcnt vmcnt(0)
	v_cmp_eq_u32_e32 vcc, v0, v1
	s_and_saveexec_b64 s[8:9], vcc
	s_cbranch_execz .LBB0_244
	s_add_u32 s12, s84, 0x4200
	s_addc_u32 s13, s85, 0
	s_mov_b32 s3, 1
	s_mov_b64 s[16:17], 0
	v_mov_b32_e32 v0, 0
	s_branch .LBB0_235

.LBB0_289:
	s_or_b64 exec, exec, s[8:9]
	v_cvt_f32_u32_e32 v4, v2
	s_waitcnt vmcnt(0)
	v_readfirstlane_b32 s3, v3
	v_sub_u32_e32 v3, 0, v2
	v_rcp_iflag_f32_e32 v4, v4
	v_add_u32_e32 v5, s3, v1
	v_mul_f32_e32 v4, 0x4f7ffffe, v4
	v_cvt_u32_f32_e32 v4, v4
	v_mul_lo_u32 v1, v3, v4
	v_mul_hi_u32 v1, v4, v1
	v_add_u32_e32 v1, v4, v1
	v_mul_hi_u32 v1, v5, v1
	v_mul_lo_u32 v3, v1, v2
	v_sub_u32_e32 v3, v5, v3
	v_add_u32_e32 v4, 1, v1
	v_cmp_ge_u32_e32 vcc, v3, v2
	s_nop 1
	v_cndmask_b32_e32 v1, v1, v4, vcc
	v_sub_u32_e32 v4, v3, v2
	v_cndmask_b32_e32 v3, v3, v4, vcc
	v_add_u32_e32 v4, 1, v1
	v_cmp_ge_u32_e32 vcc, v3, v2
	v_add_u32_e32 v3, 1, v5
	s_nop 0
	v_cndmask_b32_e32 v1, v1, v4, vcc
	v_mul_lo_u32 v4, v2, v1
	v_add_u32_e32 v2, v4, v2
	v_cmp_ne_u32_e32 vcc, v3, v2
	s_and_saveexec_b64 s[6:7], vcc
	s_xor_b64 s[6:7], exec, s[6:7]
	s_cbranch_execz .LBB0_303
	s_waitcnt lgkmcnt(0)
	v_mov_b32_e32 v0, 0x7500
	global_load_dword v0, v0, s[84:85] sc1
	s_add_u32 s14, s84, 0x7500
	s_addc_u32 s15, s85, 0
	s_waitcnt vmcnt(0)
	v_cmp_eq_u32_e32 vcc, v0, v1
	s_and_saveexec_b64 s[8:9], vcc
	s_cbranch_execz .LBB0_302
	s_add_u32 s12, s84, 0x4200
	s_addc_u32 s13, s85, 0
	s_mov_b32 s3, 1
	s_mov_b64 s[20:21], 0
	v_mov_b32_e32 v0, 0
	s_branch .LBB0_293

.LBB0_354:
	s_or_b64 exec, exec, s[8:9]
	v_cvt_f32_u32_e32 v4, v2
	s_waitcnt vmcnt(0)
	v_readfirstlane_b32 s3, v3
	v_sub_u32_e32 v3, 0, v2
	v_rcp_iflag_f32_e32 v4, v4
	v_add_u32_e32 v5, s3, v1
	v_mul_f32_e32 v4, 0x4f7ffffe, v4
	v_cvt_u32_f32_e32 v4, v4
	v_mul_lo_u32 v1, v3, v4
	v_mul_hi_u32 v1, v4, v1
	v_add_u32_e32 v1, v4, v1
	v_mul_hi_u32 v1, v5, v1
	v_mul_lo_u32 v3, v1, v2
	v_sub_u32_e32 v3, v5, v3
	v_add_u32_e32 v4, 1, v1
	v_cmp_ge_u32_e32 vcc, v3, v2
	s_nop 1
	v_cndmask_b32_e32 v1, v1, v4, vcc
	v_sub_u32_e32 v4, v3, v2
	v_cndmask_b32_e32 v3, v3, v4, vcc
	v_add_u32_e32 v4, 1, v1
	v_cmp_ge_u32_e32 vcc, v3, v2
	v_add_u32_e32 v3, 1, v5
	s_nop 0
	v_cndmask_b32_e32 v1, v1, v4, vcc
	v_mul_lo_u32 v4, v2, v1
	v_add_u32_e32 v2, v4, v2
	v_cmp_ne_u32_e32 vcc, v3, v2
	s_and_saveexec_b64 s[6:7], vcc
	s_xor_b64 s[6:7], exec, s[6:7]
	s_cbranch_execz .LBB0_368
	s_waitcnt lgkmcnt(0)
	v_mov_b32_e32 v0, 0x7500
	global_load_dword v0, v0, s[84:85] sc1
	s_add_u32 s12, s84, 0x7500
	s_addc_u32 s13, s85, 0
	s_waitcnt vmcnt(0)
	v_cmp_eq_u32_e32 vcc, v0, v1
	s_and_saveexec_b64 s[8:9], vcc
	s_cbranch_execz .LBB0_367
	s_add_u32 s10, s84, 0x4200
	s_addc_u32 s11, s85, 0
	s_mov_b32 s3, 1
	s_mov_b64 s[14:15], 0
	v_mov_b32_e32 v0, 0
	s_branch .LBB0_358

.LBB0_1084:
	s_or_b64 exec, exec, s[12:13]
	v_cvt_f32_u32_e32 v4, v2
	s_waitcnt vmcnt(0)
	v_readfirstlane_b32 s3, v3
	v_sub_u32_e32 v3, 0, v2
	v_rcp_iflag_f32_e32 v4, v4
	v_add_u32_e32 v5, s3, v1
	v_mul_f32_e32 v4, 0x4f7ffffe, v4
	v_cvt_u32_f32_e32 v4, v4
	v_mul_lo_u32 v1, v3, v4
	v_mul_hi_u32 v1, v4, v1
	v_add_u32_e32 v1, v4, v1
	v_mul_hi_u32 v1, v5, v1
	v_mul_lo_u32 v3, v1, v2
	v_sub_u32_e32 v3, v5, v3
	v_add_u32_e32 v4, 1, v1
	v_cmp_ge_u32_e32 vcc, v3, v2
	s_nop 1
	v_cndmask_b32_e32 v1, v1, v4, vcc
	v_sub_u32_e32 v4, v3, v2
	v_cndmask_b32_e32 v3, v3, v4, vcc
	v_add_u32_e32 v4, 1, v1
	v_cmp_ge_u32_e32 vcc, v3, v2
	v_add_u32_e32 v3, 1, v5
	s_nop 0
	v_cndmask_b32_e32 v1, v1, v4, vcc
	v_mul_lo_u32 v4, v2, v1
	v_add_u32_e32 v2, v4, v2
	v_cmp_ne_u32_e32 vcc, v3, v2
	s_and_saveexec_b64 s[10:11], vcc
	s_xor_b64 s[10:11], exec, s[10:11]
	s_cbranch_execz .LBB0_1098
	s_waitcnt lgkmcnt(0)
	v_mov_b32_e32 v0, 0x7500
	global_load_dword v0, v0, s[84:85] sc1
	s_add_u32 s16, s84, 0x7500
	s_addc_u32 s17, s85, 0
	s_waitcnt vmcnt(0)
	v_cmp_eq_u32_e32 vcc, v0, v1
	s_and_saveexec_b64 s[12:13], vcc
	s_cbranch_execz .LBB0_1097
	s_add_u32 s14, s84, 0x4200
	s_addc_u32 s15, s85, 0
	s_mov_b32 s3, 1
	s_mov_b64 s[18:19], 0
	v_mov_b32_e32 v0, 0
	s_branch .LBB0_1088

.LBB0_1297:
	s_or_b64 exec, exec, s[8:9]
	v_cvt_f32_u32_e32 v4, v2
	s_waitcnt vmcnt(0)
	v_readfirstlane_b32 s6, v3
	v_sub_u32_e32 v3, 0, v2
	v_rcp_iflag_f32_e32 v4, v4
	v_add_u32_e32 v5, s6, v1
	v_mul_f32_e32 v4, 0x4f7ffffe, v4
	v_cvt_u32_f32_e32 v4, v4
	v_mul_lo_u32 v1, v3, v4
	v_mul_hi_u32 v1, v4, v1
	v_add_u32_e32 v1, v4, v1
	v_mul_hi_u32 v1, v5, v1
	v_mul_lo_u32 v3, v1, v2
	v_sub_u32_e32 v3, v5, v3
	v_add_u32_e32 v4, 1, v1
	v_cmp_ge_u32_e32 vcc, v3, v2
	s_nop 1
	v_cndmask_b32_e32 v1, v1, v4, vcc
	v_sub_u32_e32 v4, v3, v2
	v_cndmask_b32_e32 v3, v3, v4, vcc
	v_add_u32_e32 v4, 1, v1
	v_cmp_ge_u32_e32 vcc, v3, v2
	v_add_u32_e32 v3, 1, v5
	s_nop 0
	v_cndmask_b32_e32 v1, v1, v4, vcc
	v_mul_lo_u32 v4, v2, v1
	v_add_u32_e32 v2, v4, v2
	v_cmp_ne_u32_e32 vcc, v3, v2
	s_and_saveexec_b64 s[6:7], vcc
	s_xor_b64 s[6:7], exec, s[6:7]
	s_cbranch_execz .LBB0_1311
	s_waitcnt lgkmcnt(0)
	v_mov_b32_e32 v0, 0x7500
	global_load_dword v0, v0, s[84:85] sc1
	s_add_u32 s12, s84, 0x7500
	s_addc_u32 s13, s85, 0
	s_waitcnt vmcnt(0)
	v_cmp_eq_u32_e32 vcc, v0, v1
	s_and_saveexec_b64 s[8:9], vcc
	s_cbranch_execz .LBB0_1310
	s_add_u32 s10, s84, 0x4200
	s_addc_u32 s11, s85, 0
	s_mov_b32 s22, 1
	s_mov_b64 s[14:15], 0
	v_mov_b32_e32 v0, 0
	s_branch .LBB0_1301

.LBB0_1374:
	s_or_b64 exec, exec, s[6:7]
	v_cvt_f32_u32_e32 v4, v2
	s_waitcnt vmcnt(0)
	v_readfirstlane_b32 s4, v3
	v_sub_u32_e32 v3, 0, v2
	v_rcp_iflag_f32_e32 v4, v4
	v_add_u32_e32 v5, s4, v1
	v_mul_f32_e32 v4, 0x4f7ffffe, v4
	v_cvt_u32_f32_e32 v4, v4
	v_mul_lo_u32 v1, v3, v4
	v_mul_hi_u32 v1, v4, v1
	v_add_u32_e32 v1, v4, v1
	v_mul_hi_u32 v1, v5, v1
	v_mul_lo_u32 v3, v1, v2
	v_sub_u32_e32 v3, v5, v3
	v_add_u32_e32 v4, 1, v1
	v_cmp_ge_u32_e32 vcc, v3, v2
	s_nop 1
	v_cndmask_b32_e32 v1, v1, v4, vcc
	v_sub_u32_e32 v4, v3, v2
	v_cndmask_b32_e32 v3, v3, v4, vcc
	v_add_u32_e32 v4, 1, v1
	v_cmp_ge_u32_e32 vcc, v3, v2
	v_add_u32_e32 v3, 1, v5
	s_nop 0
	v_cndmask_b32_e32 v1, v1, v4, vcc
	v_mul_lo_u32 v4, v2, v1
	v_add_u32_e32 v2, v4, v2
	v_cmp_ne_u32_e32 vcc, v3, v2
	s_and_saveexec_b64 s[4:5], vcc
	s_xor_b64 s[4:5], exec, s[4:5]
	s_cbranch_execz .LBB0_1388
	s_waitcnt lgkmcnt(0)
	v_mov_b32_e32 v0, 0x7500
	global_load_dword v0, v0, s[84:85] sc1
	s_add_u32 s10, s84, 0x7500
	s_addc_u32 s11, s85, 0
	s_waitcnt vmcnt(0)
	v_cmp_eq_u32_e32 vcc, v0, v1
	s_and_saveexec_b64 s[6:7], vcc
	s_cbranch_execz .LBB0_1387
	s_add_u32 s8, s84, 0x4200
	s_addc_u32 s9, s85, 0
	s_mov_b32 s22, 1
	s_mov_b64 s[12:13], 0
	v_mov_b32_e32 v0, 0
	s_branch .LBB0_1378
